# adds software-pipelined LDS reads in GLA step C (in-place q/k scaling, A blocks, o accumulation)
# baseline (speedup 1.0000x reference)
; #define LAS __attribute__((address_space(3)))
; __device__ __forceinline__ void gla_stage_glr(LAS float* glrs, const float* glr, int R0, int tid) { if (tid < 256) *(LAS f32x4*)(glrs + tid * 4) = *(const f32x4*)(glr + (size_t)R0 * 16 + tid * 4); }
; __device__ __forceinline__ void gla_logdecay(float (&b)[16], float& blast, const LAS float* glrs, const float (&wcol)[16], const float bias, int d, int g, LAS float* tot) {
;     ...
;     for (int ii = 0; ii < 16; ++ii) { const LAS f32x4* gr = (const LAS f32x4*)(glrs + (16 * g + ii) * 16); float z = bias;
; #pragma unroll
;         for (int r4 = 0; r4 < 4; ++r4) { const f32x4 gv = gr[r4]; z += gv[0] * wcol[4 * r4] + gv[1] * wcol[4 * r4 + 1] + gv[2] * wcol[4 * r4 + 2] + gv[3] * wcol[4 * r4 + 3]; }
;         const float la = -(fmaxf(-z, 0.f) + __logf(1.0f + __expf(-fabsf(z)))) * (1.0f / 16.0f);
;         run += la; b[ii] = run; }
; __device__ __forceinline__ void gla_stepC(LAS unsigned char* lds, int item, const bf16* proj, const bf16* vtg, const float* glr, const float* W2, const float* b2, const bf16* sT, const float* gout, bf16* mix) {
;     ...
;     gla_stage_glr(glrs, glr, R0, tid);
;     gla_stage_raw(QE, proj + (size_t)R0 * PROJW + 3072 + hg * 128, PROJW, tid);
;     gla_stage_raw(KE, proj + (size_t)R0 * PROJW + 3584 + hg * 128, PROJW, tid);
;     gla_load_vt(VT, vtg + (size_t)(bb * 4 + hg) * 256 * SEQ + n * 64);
;     __syncthreads();
.LBB0_80:
	s_or_b64 exec, exec, s[40:41]
	s_mul_i32 s17, s36, 0x3000
	s_mul_hi_i32 s16, s36, 0x3000
	s_add_u32 s17, s38, s17
	s_addc_u32 s16, s39, s16
	s_lshl_b32 s14, s14, 1
	s_add_u32 s14, s17, s14
	s_addc_u32 s22, s16, 0
	s_add_u32 s16, s14, 0x1800
	s_addc_u32 s17, s22, 0
	v_ashrrev_i32_e32 v94, 3, v55
	v_mov_b64_e32 v[86:87], s[16:17]
	v_lshlrev_b32_e32 v88, 4, v55
	v_mad_i64_i32 v[86:87], s[16:17], v94, s97, v[86:87]
	v_and_b32_e32 v90, 0x70, v88
	v_mov_b32_e32 v91, v153
	v_lshl_add_u64 v[92:93], v[86:87], 0, v[90:91]
	global_load_dwordx4 v[108:111], v[92:93], off
	v_mul_lo_u32 v95, v94, s94
	v_add3_u32 v95, 0, v95, v90
	s_add_u32 s16, s14, 0x1c00
	s_addc_u32 s17, s22, 0
	s_lshl_b32 s14, s15, 2
	s_or_b32 s14, s14, s46
	s_ashr_i32 s15, s14, 31
	s_lshl_b64 s[14:15], s[14:15], 20
	s_add_u32 s14, s71, s14
	s_addc_u32 s15, s80, s15
	s_lshl_b32 s0, s0, 1
	s_add_u32 s14, s14, s0
	s_addc_u32 s15, s15, 0
	v_ashrrev_i32_e32 v41, 7, v55
	s_mov_b32 s0, 0xbd800000
	v_lshlrev_b32_e32 v63, 2, v61
	global_load_dwordx4 v[112:115], v[92:93], off offset:128
	v_mov_b64_e32 v[86:87], s[16:17]
	v_mad_i64_i32 v[86:87], s[16:17], v94, s97, v[86:87]
	v_lshl_add_u64 v[90:91], v[86:87], 0, v[90:91]
	global_load_dwordx4 v[116:119], v[90:91], off
	s_movk_i32 s16, 0x90
	global_load_dwordx4 v[120:123], v[90:91], off offset:128
	v_mov_b32_e32 v90, v176
	v_mov_b32_e32 v91, v153
	s_nop 0
	v_ashrrev_i32_e32 v86, 1, v90
	v_ashrrev_i32_e32 v87, 31, v86
	v_lshlrev_b64 v[88:89], 12, v[86:87]
	v_lshlrev_b32_e32 v87, 6, v90
	v_lshl_add_u64 v[88:89], s[14:15], 0, v[88:89]
	v_and_b32_e32 v90, 64, v87
	v_lshl_add_u64 v[98:99], v[88:89], 0, v[90:91]
	v_mul_lo_u32 v86, v86, s16
	v_add3_u32 v102, 0, v86, v90
	global_load_dwordx4 v[128:131], v[98:99], off offset:48
	global_load_dwordx4 v[132:135], v[98:99], off offset:32
	global_load_dwordx4 v[136:139], v[98:99], off offset:16
	global_load_dwordx4 v[140:143], v[98:99], off
	v_cmp_gt_i32_e32 vcc, 0x100, v55
	s_waitcnt vmcnt(0)
	s_nop 0
	s_and_saveexec_b64 s[40:41], vcc
	ds_write_b128 v124, v[104:107]
	s_or_b64 exec, exec, s[40:41]
	ds_write_b128 v95, v[108:111]
	ds_write_b128 v95, v[112:115] offset:128
	ds_write_b128 v95, v[116:119] offset:18432
	ds_write_b128 v95, v[120:123] offset:18560
	ds_write_b128 v102, v[140:143] offset:36864
	ds_write_b128 v102, v[136:139] offset:36880
	ds_write_b128 v102, v[132:135] offset:36896
	ds_write_b128 v102, v[128:131] offset:36912
	v_lshl_add_u32 v86, v41, 10, 0
	v_add_u32_e32 v87, 0x15400, v86
	s_waitcnt lgkmcnt(0)
	s_barrier
	ds_read_b128 v[114:117], v87
	ds_read_b128 v[118:121], v87 offset:16
	ds_read_b128 v[122:125], v87 offset:32
	ds_read_b128 v[126:129], v87 offset:48
	ds_read_b128 v[130:133], v87 offset:64
	ds_read_b128 v[134:137], v87 offset:80
	ds_read_b128 v[138:141], v87 offset:96
	ds_read_b128 v[142:145], v87 offset:112
	s_waitcnt lgkmcnt(7)
	v_mul_f32_e32 v86, v80, v115
	v_fmac_f32_e32 v86, v79, v114
	s_waitcnt lgkmcnt(6)
	v_mul_f32_e32 v88, v72, v119
	v_fmac_f32_e32 v86, v83, v116
	v_fmac_f32_e32 v88, v71, v118
	v_fmac_f32_e32 v86, v84, v117
	ds_read_b128 v[114:117], v87 offset:128
	v_fmac_f32_e32 v88, v77, v120
	v_add_f32_e32 v86, v85, v86
	v_fmac_f32_e32 v88, v78, v121
	ds_read_b128 v[118:121], v87 offset:144
	v_add_f32_e32 v86, v86, v88
	s_waitcnt lgkmcnt(7)
	v_mul_f32_e32 v88, v75, v123
	v_fmac_f32_e32 v88, v73, v122
	v_fmac_f32_e32 v88, v81, v124
	v_fmac_f32_e32 v88, v82, v125
	ds_read_b128 v[122:125], v87 offset:160
	v_add_f32_e32 v86, v86, v88
	s_waitcnt lgkmcnt(7)
	v_mul_f32_e32 v88, v70, v127
	v_fmac_f32_e32 v88, v67, v126
	v_fmac_f32_e32 v88, v76, v128
	v_fmac_f32_e32 v88, v74, v129
	ds_read_b128 v[126:129], v87 offset:176
	v_add_f32_e32 v86, v86, v88
	v_max_f32_e64 v88, -v86, 0
	v_mul_f32_e64 v86, |v86|, s64
	v_exp_f32_e32 v86, v86
	s_nop 0
	v_add_f32_e32 v86, 1.0, v86
	v_cmp_gt_f32_e32 vcc, s65, v86
	s_nop 1
	v_cndmask_b32_e64 v89, 0, 32, vcc
	v_ldexp_f32 v86, v86, v89
	v_log_f32_e32 v86, v86
	s_nop 0
	v_mul_f32_e32 v89, 0x3f317217, v86
	v_fma_f32 v89, v86, s66, -v89
	v_fmac_f32_e32 v89, 0x3377d1cf, v86
	v_fmac_f32_e32 v89, 0x3f317217, v86
	v_cmp_lt_f32_e64 s[40:41], |v86|, s67
	s_nop 1
	v_cndmask_b32_e64 v86, v86, v89, s[40:41]
	v_cndmask_b32_e32 v89, 0, v252, vcc
	v_sub_f32_e32 v86, v86, v89
	v_add_f32_e32 v86, v88, v86
	v_fma_f32 v86, v86, s0, 0
	s_movk_i32 s0, 0x900
	s_waitcnt lgkmcnt(7)
	v_mul_f32_e32 v89, v80, v131
	v_fmac_f32_e32 v89, v79, v130
	v_fmac_f32_e32 v89, v83, v132
	v_fmac_f32_e32 v89, v84, v133
	ds_read_b128 v[130:133], v87 offset:192
	v_add_f32_e32 v92, v85, v89
	s_waitcnt lgkmcnt(7)
	v_mul_f32_e32 v89, v72, v135
	v_fmac_f32_e32 v89, v71, v134
	v_fmac_f32_e32 v89, v77, v136
	v_fmac_f32_e32 v89, v78, v137
	ds_read_b128 v[134:137], v87 offset:208
	v_add_f32_e32 v92, v92, v89
	s_waitcnt lgkmcnt(7)
	v_mul_f32_e32 v89, v75, v139
	v_fmac_f32_e32 v89, v73, v138
	v_fmac_f32_e32 v89, v81, v140
	v_fmac_f32_e32 v89, v82, v141
	ds_read_b128 v[138:141], v87 offset:224
	v_add_f32_e32 v92, v92, v89
	s_waitcnt lgkmcnt(7)
	v_mul_f32_e32 v89, v70, v143
	v_fmac_f32_e32 v89, v67, v142
	v_fmac_f32_e32 v89, v76, v144
	v_fmac_f32_e32 v89, v74, v145
	ds_read_b128 v[142:145], v87 offset:240
	v_add_f32_e32 v88, v92, v89
	v_max_f32_e64 v89, -v88, 0
	v_mul_f32_e64 v88, |v88|, s64
	v_exp_f32_e32 v88, v88
	s_nop 0
	v_add_f32_e32 v88, 1.0, v88
	v_cmp_gt_f32_e32 vcc, s65, v88
	s_nop 1
	v_cndmask_b32_e64 v90, 0, 32, vcc
	v_ldexp_f32 v88, v88, v90
	v_log_f32_e32 v88, v88
	s_nop 0
	v_mul_f32_e32 v90, 0x3f317217, v88
	v_fma_f32 v90, v88, s66, -v90
	v_fmac_f32_e32 v90, 0x3377d1cf, v88
	v_fmac_f32_e32 v90, 0x3f317217, v88
	v_cmp_lt_f32_e64 s[40:41], |v88|, s67
	s_nop 1
	v_cndmask_b32_e64 v88, v88, v90, s[40:41]
	v_cndmask_b32_e32 v90, 0, v252, vcc
	v_sub_f32_e32 v88, v88, v90
	v_add_f32_e32 v88, v89, v88
	v_fmamk_f32 v88, v88, 0xbd800000, v86
	s_waitcnt lgkmcnt(7)
; #define LAS __attribute__((address_space(3)))
; __device__ __forceinline__ void gla_logdecay(float (&b)[16], float& blast, const LAS float* glrs, const float (&wcol)[16], const float bias, int d, int g, LAS float* tot) {
;     ...
;     for (int ii = 0; ii < 16; ++ii) { const LAS f32x4* gr = (const LAS f32x4*)(glrs + (16 * g + ii) * 16); float z = bias;
; #pragma unroll
;         for (int r4 = 0; r4 < 4; ++r4) { const f32x4 gv = gr[r4]; z += gv[0] * wcol[4 * r4] + gv[1] * wcol[4 * r4 + 1] + gv[2] * wcol[4 * r4 + 2] + gv[3] * wcol[4 * r4 + 3]; }
;         const float la = -(fmaxf(-z, 0.f) + __logf(1.0f + __expf(-fabsf(z)))) * (1.0f / 16.0f);
;         run += la; b[ii] = run; }
	v_mul_f32_e32 v89, v80, v115
	v_fmac_f32_e32 v89, v79, v114
	v_fmac_f32_e32 v89, v83, v116
	v_fmac_f32_e32 v89, v84, v117
	ds_read_b128 v[114:117], v87 offset:256
	v_add_f32_e32 v89, v85, v89
	s_waitcnt lgkmcnt(7)
	v_mul_f32_e32 v91, v72, v119
	v_fmac_f32_e32 v91, v71, v118
	v_fmac_f32_e32 v91, v77, v120
	v_fmac_f32_e32 v91, v78, v121
	ds_read_b128 v[118:121], v87 offset:272
	v_add_f32_e32 v89, v89, v91
	s_waitcnt lgkmcnt(7)
	v_mul_f32_e32 v91, v75, v123
	v_fmac_f32_e32 v91, v73, v122
	v_fmac_f32_e32 v91, v81, v124
	v_fmac_f32_e32 v91, v82, v125
	ds_read_b128 v[122:125], v87 offset:288
	v_add_f32_e32 v89, v89, v91
	s_waitcnt lgkmcnt(7)
	v_mul_f32_e32 v91, v70, v127
	v_fmac_f32_e32 v91, v67, v126
	v_fmac_f32_e32 v91, v76, v128
	v_fmac_f32_e32 v91, v74, v129
	ds_read_b128 v[126:129], v87 offset:304
	v_add_f32_e32 v89, v89, v91
	v_max_f32_e64 v90, -v89, 0
	v_mul_f32_e64 v89, |v89|, s64
	v_exp_f32_e32 v89, v89
	s_nop 0
	v_add_f32_e32 v89, 1.0, v89
	v_cmp_gt_f32_e32 vcc, s65, v89
	s_nop 1
	v_cndmask_b32_e64 v91, 0, 32, vcc
	v_ldexp_f32 v89, v89, v91
	v_log_f32_e32 v89, v89
	s_nop 0
	v_mul_f32_e32 v91, 0x3f317217, v89
	v_fma_f32 v91, v89, s66, -v91
	v_fmac_f32_e32 v91, 0x3377d1cf, v89
	v_fmac_f32_e32 v91, 0x3f317217, v89
	v_cmp_lt_f32_e64 s[40:41], |v89|, s67
	s_nop 1
	v_cndmask_b32_e64 v89, v89, v91, s[40:41]
	v_cndmask_b32_e32 v91, 0, v252, vcc
	v_sub_f32_e32 v89, v89, v91
	v_add_f32_e32 v89, v90, v89
	v_fmamk_f32 v89, v89, 0xbd800000, v88
	s_waitcnt lgkmcnt(7)
	v_mul_f32_e32 v91, v80, v131
	v_fmac_f32_e32 v91, v79, v130
	v_fmac_f32_e32 v91, v83, v132
	v_fmac_f32_e32 v91, v84, v133
	ds_read_b128 v[130:133], v87 offset:320
	v_add_f32_e32 v94, v85, v91
	s_waitcnt lgkmcnt(7)
	v_mul_f32_e32 v91, v72, v135
	v_fmac_f32_e32 v91, v71, v134
	v_fmac_f32_e32 v91, v77, v136
	v_fmac_f32_e32 v91, v78, v137
	ds_read_b128 v[134:137], v87 offset:336
	v_add_f32_e32 v94, v94, v91
	s_waitcnt lgkmcnt(7)
	v_mul_f32_e32 v91, v75, v139
	v_fmac_f32_e32 v91, v73, v138
	v_fmac_f32_e32 v91, v81, v140
	v_fmac_f32_e32 v91, v82, v141
	ds_read_b128 v[138:141], v87 offset:352
	v_add_f32_e32 v94, v94, v91
	s_waitcnt lgkmcnt(7)
	v_mul_f32_e32 v91, v70, v143
	v_fmac_f32_e32 v91, v67, v142
	v_fmac_f32_e32 v91, v76, v144
	v_fmac_f32_e32 v91, v74, v145
	ds_read_b128 v[142:145], v87 offset:368
	v_add_f32_e32 v90, v94, v91
	v_max_f32_e64 v91, -v90, 0
	v_mul_f32_e64 v90, |v90|, s64
	v_exp_f32_e32 v90, v90
	s_nop 0
	v_add_f32_e32 v90, 1.0, v90
	v_cmp_gt_f32_e32 vcc, s65, v90
	s_nop 1
	v_cndmask_b32_e64 v92, 0, 32, vcc
	v_ldexp_f32 v90, v90, v92
	v_log_f32_e32 v90, v90
	s_nop 0
	v_mul_f32_e32 v92, 0x3f317217, v90
	v_fma_f32 v92, v90, s66, -v92
	v_fmac_f32_e32 v92, 0x3377d1cf, v90
	v_fmac_f32_e32 v92, 0x3f317217, v90
	v_cmp_lt_f32_e64 s[40:41], |v90|, s67
	s_nop 1
	v_cndmask_b32_e64 v90, v90, v92, s[40:41]
	v_cndmask_b32_e32 v92, 0, v252, vcc
	v_sub_f32_e32 v90, v90, v92
	v_add_f32_e32 v90, v91, v90
	v_fmamk_f32 v90, v90, 0xbd800000, v89
	s_waitcnt lgkmcnt(7)
	v_mul_f32_e32 v91, v80, v115
	v_fmac_f32_e32 v91, v79, v114
	v_fmac_f32_e32 v91, v83, v116
	v_fmac_f32_e32 v91, v84, v117
	ds_read_b128 v[114:117], v87 offset:384
	v_add_f32_e32 v91, v85, v91
	s_waitcnt lgkmcnt(7)
	v_mul_f32_e32 v93, v72, v119
	v_fmac_f32_e32 v93, v71, v118
	v_fmac_f32_e32 v93, v77, v120
	v_fmac_f32_e32 v93, v78, v121
	ds_read_b128 v[118:121], v87 offset:400
	v_add_f32_e32 v91, v91, v93
	s_waitcnt lgkmcnt(7)
	v_mul_f32_e32 v93, v75, v123
	v_fmac_f32_e32 v93, v73, v122
	v_fmac_f32_e32 v93, v81, v124
	v_fmac_f32_e32 v93, v82, v125
	ds_read_b128 v[122:125], v87 offset:416
	v_add_f32_e32 v91, v91, v93
	s_waitcnt lgkmcnt(7)
	v_mul_f32_e32 v93, v70, v127
	v_fmac_f32_e32 v93, v67, v126
	v_fmac_f32_e32 v93, v76, v128
	v_fmac_f32_e32 v93, v74, v129
	ds_read_b128 v[126:129], v87 offset:432
	v_add_f32_e32 v91, v91, v93
	v_max_f32_e64 v92, -v91, 0
	v_mul_f32_e64 v91, |v91|, s64
	v_exp_f32_e32 v91, v91
	s_nop 0
	v_add_f32_e32 v91, 1.0, v91
	v_cmp_gt_f32_e32 vcc, s65, v91
	s_nop 1
	v_cndmask_b32_e64 v93, 0, 32, vcc
	v_ldexp_f32 v91, v91, v93
	v_log_f32_e32 v91, v91
	s_nop 0
	v_mul_f32_e32 v93, 0x3f317217, v91
	v_fma_f32 v93, v91, s66, -v93
	v_fmac_f32_e32 v93, 0x3377d1cf, v91
	v_fmac_f32_e32 v93, 0x3f317217, v91
	v_cmp_lt_f32_e64 s[40:41], |v91|, s67
	s_nop 1
	v_cndmask_b32_e64 v91, v91, v93, s[40:41]
	v_cndmask_b32_e32 v93, 0, v252, vcc
	v_sub_f32_e32 v91, v91, v93
	v_add_f32_e32 v91, v92, v91
	v_fmamk_f32 v91, v91, 0xbd800000, v90
	s_waitcnt lgkmcnt(7)
	v_mul_f32_e32 v93, v80, v131
	v_fmac_f32_e32 v93, v79, v130
	v_fmac_f32_e32 v93, v83, v132
	v_fmac_f32_e32 v93, v84, v133
	ds_read_b128 v[130:133], v87 offset:448
	v_add_f32_e32 v96, v85, v93
	s_waitcnt lgkmcnt(7)
	v_mul_f32_e32 v93, v72, v135
	v_fmac_f32_e32 v93, v71, v134
	v_fmac_f32_e32 v93, v77, v136
	v_fmac_f32_e32 v93, v78, v137
	ds_read_b128 v[134:137], v87 offset:464
	v_add_f32_e32 v96, v96, v93
	s_waitcnt lgkmcnt(7)
	v_mul_f32_e32 v93, v75, v139
	v_fmac_f32_e32 v93, v73, v138
	v_fmac_f32_e32 v93, v81, v140
	v_fmac_f32_e32 v93, v82, v141
	ds_read_b128 v[138:141], v87 offset:480
	v_add_f32_e32 v96, v96, v93
	s_waitcnt lgkmcnt(7)
	v_mul_f32_e32 v93, v70, v143
	v_fmac_f32_e32 v93, v67, v142
	v_fmac_f32_e32 v93, v76, v144
	v_fmac_f32_e32 v93, v74, v145
	ds_read_b128 v[142:145], v87 offset:496
	v_add_f32_e32 v92, v96, v93
	v_max_f32_e64 v93, -v92, 0
	v_mul_f32_e64 v92, |v92|, s64
	v_exp_f32_e32 v92, v92
	s_nop 0
	v_add_f32_e32 v92, 1.0, v92
	v_cmp_gt_f32_e32 vcc, s65, v92
	s_nop 1
	v_cndmask_b32_e64 v94, 0, 32, vcc
	v_ldexp_f32 v92, v92, v94
	v_log_f32_e32 v92, v92
	s_nop 0
	v_mul_f32_e32 v94, 0x3f317217, v92
	v_fma_f32 v94, v92, s66, -v94
	v_fmac_f32_e32 v94, 0x3377d1cf, v92
	v_fmac_f32_e32 v94, 0x3f317217, v92
	v_cmp_lt_f32_e64 s[40:41], |v92|, s67
	s_nop 1
	v_cndmask_b32_e64 v92, v92, v94, s[40:41]
	v_cndmask_b32_e32 v94, 0, v252, vcc
	v_sub_f32_e32 v92, v92, v94
	v_add_f32_e32 v92, v93, v92
	v_fmamk_f32 v92, v92, 0xbd800000, v91
	s_waitcnt lgkmcnt(7)
; #define LAS __attribute__((address_space(3)))
; __device__ __forceinline__ void gla_logdecay(float (&b)[16], float& blast, const LAS float* glrs, const float (&wcol)[16], const float bias, int d, int g, LAS float* tot) {
;     ...
;     for (int ii = 0; ii < 16; ++ii) { const LAS f32x4* gr = (const LAS f32x4*)(glrs + (16 * g + ii) * 16); float z = bias;
; #pragma unroll
;         for (int r4 = 0; r4 < 4; ++r4) { const f32x4 gv = gr[r4]; z += gv[0] * wcol[4 * r4] + gv[1] * wcol[4 * r4 + 1] + gv[2] * wcol[4 * r4 + 2] + gv[3] * wcol[4 * r4 + 3]; }
;         const float la = -(fmaxf(-z, 0.f) + __logf(1.0f + __expf(-fabsf(z)))) * (1.0f / 16.0f);
;         run += la; b[ii] = run; }
	v_mul_f32_e32 v93, v80, v115
	v_fmac_f32_e32 v93, v79, v114
	v_fmac_f32_e32 v93, v83, v116
	v_fmac_f32_e32 v93, v84, v117
	ds_read_b128 v[114:117], v87 offset:512
	v_add_f32_e32 v93, v85, v93
	s_waitcnt lgkmcnt(7)
	v_mul_f32_e32 v95, v72, v119
	v_fmac_f32_e32 v95, v71, v118
	v_fmac_f32_e32 v95, v77, v120
	v_fmac_f32_e32 v95, v78, v121
	ds_read_b128 v[118:121], v87 offset:528
	v_add_f32_e32 v93, v93, v95
	s_waitcnt lgkmcnt(7)
	v_mul_f32_e32 v95, v75, v123
	v_fmac_f32_e32 v95, v73, v122
	v_fmac_f32_e32 v95, v81, v124
	v_fmac_f32_e32 v95, v82, v125
	ds_read_b128 v[122:125], v87 offset:544
	v_add_f32_e32 v93, v93, v95
	s_waitcnt lgkmcnt(7)
	v_mul_f32_e32 v95, v70, v127
	v_fmac_f32_e32 v95, v67, v126
	v_fmac_f32_e32 v95, v76, v128
	v_fmac_f32_e32 v95, v74, v129
	ds_read_b128 v[126:129], v87 offset:560
	v_add_f32_e32 v93, v93, v95
	v_max_f32_e64 v94, -v93, 0
	v_mul_f32_e64 v93, |v93|, s64
	v_exp_f32_e32 v93, v93
	s_nop 0
	v_add_f32_e32 v93, 1.0, v93
	v_cmp_gt_f32_e32 vcc, s65, v93
	s_nop 1
	v_cndmask_b32_e64 v95, 0, 32, vcc
	v_ldexp_f32 v93, v93, v95
	v_log_f32_e32 v93, v93
	s_nop 0
	v_mul_f32_e32 v95, 0x3f317217, v93
	v_fma_f32 v95, v93, s66, -v95
	v_fmac_f32_e32 v95, 0x3377d1cf, v93
	v_fmac_f32_e32 v95, 0x3f317217, v93
	v_cmp_lt_f32_e64 s[40:41], |v93|, s67
	s_nop 1
	v_cndmask_b32_e64 v93, v93, v95, s[40:41]
	v_cndmask_b32_e32 v95, 0, v252, vcc
	v_sub_f32_e32 v93, v93, v95
	v_add_f32_e32 v93, v94, v93
	v_fmamk_f32 v93, v93, 0xbd800000, v92
	s_waitcnt lgkmcnt(7)
	v_mul_f32_e32 v95, v80, v131
	v_fmac_f32_e32 v95, v79, v130
	v_fmac_f32_e32 v95, v83, v132
	v_fmac_f32_e32 v95, v84, v133
	ds_read_b128 v[130:133], v87 offset:576
	v_add_f32_e32 v98, v85, v95
	s_waitcnt lgkmcnt(7)
	v_mul_f32_e32 v95, v72, v135
	v_fmac_f32_e32 v95, v71, v134
	v_fmac_f32_e32 v95, v77, v136
	v_fmac_f32_e32 v95, v78, v137
	ds_read_b128 v[134:137], v87 offset:592
	v_add_f32_e32 v98, v98, v95
	s_waitcnt lgkmcnt(7)
	v_mul_f32_e32 v95, v75, v139
	v_fmac_f32_e32 v95, v73, v138
	v_fmac_f32_e32 v95, v81, v140
	v_fmac_f32_e32 v95, v82, v141
	ds_read_b128 v[138:141], v87 offset:608
	v_add_f32_e32 v98, v98, v95
	s_waitcnt lgkmcnt(7)
	v_mul_f32_e32 v95, v70, v143
	v_fmac_f32_e32 v95, v67, v142
	v_fmac_f32_e32 v95, v76, v144
	v_fmac_f32_e32 v95, v74, v145
	ds_read_b128 v[142:145], v87 offset:624
	v_add_f32_e32 v94, v98, v95
	v_max_f32_e64 v95, -v94, 0
	v_mul_f32_e64 v94, |v94|, s64
	v_exp_f32_e32 v94, v94
	s_nop 0
	v_add_f32_e32 v94, 1.0, v94
	v_cmp_gt_f32_e32 vcc, s65, v94
	s_nop 1
	v_cndmask_b32_e64 v96, 0, 32, vcc
	v_ldexp_f32 v94, v94, v96
	v_log_f32_e32 v94, v94
	s_nop 0
	v_mul_f32_e32 v96, 0x3f317217, v94
	v_fma_f32 v96, v94, s66, -v96
	v_fmac_f32_e32 v96, 0x3377d1cf, v94
	v_fmac_f32_e32 v96, 0x3f317217, v94
	v_cmp_lt_f32_e64 s[40:41], |v94|, s67
	s_nop 1
	v_cndmask_b32_e64 v94, v94, v96, s[40:41]
	v_cndmask_b32_e32 v96, 0, v252, vcc
	v_sub_f32_e32 v94, v94, v96
	v_add_f32_e32 v94, v95, v94
	v_fmamk_f32 v94, v94, 0xbd800000, v93
	s_waitcnt lgkmcnt(7)
	v_mul_f32_e32 v95, v80, v115
	v_fmac_f32_e32 v95, v79, v114
	v_fmac_f32_e32 v95, v83, v116
	v_fmac_f32_e32 v95, v84, v117
	ds_read_b128 v[114:117], v87 offset:640
	v_add_f32_e32 v95, v85, v95
	s_waitcnt lgkmcnt(7)
	v_mul_f32_e32 v97, v72, v119
	v_fmac_f32_e32 v97, v71, v118
	v_fmac_f32_e32 v97, v77, v120
	v_fmac_f32_e32 v97, v78, v121
	ds_read_b128 v[118:121], v87 offset:656
	v_add_f32_e32 v95, v95, v97
	s_waitcnt lgkmcnt(7)
	v_mul_f32_e32 v97, v75, v123
	v_fmac_f32_e32 v97, v73, v122
	v_fmac_f32_e32 v97, v81, v124
	v_fmac_f32_e32 v97, v82, v125
	ds_read_b128 v[122:125], v87 offset:672
	v_add_f32_e32 v95, v95, v97
	s_waitcnt lgkmcnt(7)
	v_mul_f32_e32 v97, v70, v127
	v_fmac_f32_e32 v97, v67, v126
	v_fmac_f32_e32 v97, v76, v128
	v_fmac_f32_e32 v97, v74, v129
	ds_read_b128 v[126:129], v87 offset:688
	v_add_f32_e32 v95, v95, v97
	v_max_f32_e64 v96, -v95, 0
	v_mul_f32_e64 v95, |v95|, s64
	v_exp_f32_e32 v95, v95
	s_nop 0
	v_add_f32_e32 v95, 1.0, v95
	v_cmp_gt_f32_e32 vcc, s65, v95
	s_nop 1
	v_cndmask_b32_e64 v97, 0, 32, vcc
	v_ldexp_f32 v95, v95, v97
	v_log_f32_e32 v95, v95
	s_nop 0
	v_mul_f32_e32 v97, 0x3f317217, v95
	v_fma_f32 v97, v95, s66, -v97
	v_fmac_f32_e32 v97, 0x3377d1cf, v95
	v_fmac_f32_e32 v97, 0x3f317217, v95
	v_cmp_lt_f32_e64 s[40:41], |v95|, s67
	s_nop 1
	v_cndmask_b32_e64 v95, v95, v97, s[40:41]
	v_cndmask_b32_e32 v97, 0, v252, vcc
	v_sub_f32_e32 v95, v95, v97
	v_add_f32_e32 v95, v96, v95
	v_fmamk_f32 v95, v95, 0xbd800000, v94
	s_waitcnt lgkmcnt(7)
	v_mul_f32_e32 v97, v80, v131
	v_fmac_f32_e32 v97, v79, v130
	v_fmac_f32_e32 v97, v83, v132
	v_fmac_f32_e32 v97, v84, v133
	ds_read_b128 v[130:133], v87 offset:704
	v_add_f32_e32 v100, v85, v97
	s_waitcnt lgkmcnt(7)
	v_mul_f32_e32 v97, v72, v135
	v_fmac_f32_e32 v97, v71, v134
	v_fmac_f32_e32 v97, v77, v136
	v_fmac_f32_e32 v97, v78, v137
	ds_read_b128 v[134:137], v87 offset:720
	v_add_f32_e32 v100, v100, v97
	s_waitcnt lgkmcnt(7)
	v_mul_f32_e32 v97, v75, v139
	v_fmac_f32_e32 v97, v73, v138
	v_fmac_f32_e32 v97, v81, v140
	v_fmac_f32_e32 v97, v82, v141
	ds_read_b128 v[138:141], v87 offset:736
	v_add_f32_e32 v100, v100, v97
	s_waitcnt lgkmcnt(7)
	v_mul_f32_e32 v97, v70, v143
	v_fmac_f32_e32 v97, v67, v142
	v_fmac_f32_e32 v97, v76, v144
	v_fmac_f32_e32 v97, v74, v145
	ds_read_b128 v[142:145], v87 offset:752
	v_add_f32_e32 v96, v100, v97
	v_max_f32_e64 v97, -v96, 0
	v_mul_f32_e64 v96, |v96|, s64
	v_exp_f32_e32 v96, v96
	s_nop 0
	v_add_f32_e32 v96, 1.0, v96
	v_cmp_gt_f32_e32 vcc, s65, v96
	s_nop 1
	v_cndmask_b32_e64 v98, 0, 32, vcc
	v_ldexp_f32 v96, v96, v98
	v_log_f32_e32 v96, v96
	s_nop 0
	v_mul_f32_e32 v98, 0x3f317217, v96
	v_fma_f32 v98, v96, s66, -v98
	v_fmac_f32_e32 v98, 0x3377d1cf, v96
	v_fmac_f32_e32 v98, 0x3f317217, v96
	v_cmp_lt_f32_e64 s[40:41], |v96|, s67
	s_nop 1
	v_cndmask_b32_e64 v96, v96, v98, s[40:41]
	v_cndmask_b32_e32 v98, 0, v252, vcc
	v_sub_f32_e32 v96, v96, v98
	v_add_f32_e32 v96, v97, v96
	v_fmamk_f32 v96, v96, 0xbd800000, v95
	s_waitcnt lgkmcnt(7)
; #define LAS __attribute__((address_space(3)))
; __device__ __forceinline__ void gla_logdecay(float (&b)[16], float& blast, const LAS float* glrs, const float (&wcol)[16], const float bias, int d, int g, LAS float* tot) {
;     ...
;     for (int ii = 0; ii < 16; ++ii) { const LAS f32x4* gr = (const LAS f32x4*)(glrs + (16 * g + ii) * 16); float z = bias;
; #pragma unroll
;         for (int r4 = 0; r4 < 4; ++r4) { const f32x4 gv = gr[r4]; z += gv[0] * wcol[4 * r4] + gv[1] * wcol[4 * r4 + 1] + gv[2] * wcol[4 * r4 + 2] + gv[3] * wcol[4 * r4 + 3]; }
;         const float la = -(fmaxf(-z, 0.f) + __logf(1.0f + __expf(-fabsf(z)))) * (1.0f / 16.0f);
;         run += la; b[ii] = run; }
	v_mul_f32_e32 v97, v80, v115
	v_fmac_f32_e32 v97, v79, v114
	v_fmac_f32_e32 v97, v83, v116
	v_fmac_f32_e32 v97, v84, v117
	ds_read_b128 v[114:117], v87 offset:768
	v_add_f32_e32 v97, v85, v97
	s_waitcnt lgkmcnt(7)
	v_mul_f32_e32 v99, v72, v119
	v_fmac_f32_e32 v99, v71, v118
	v_fmac_f32_e32 v99, v77, v120
	v_fmac_f32_e32 v99, v78, v121
	ds_read_b128 v[118:121], v87 offset:784
	v_add_f32_e32 v97, v97, v99
	s_waitcnt lgkmcnt(7)
	v_mul_f32_e32 v99, v75, v123
	v_fmac_f32_e32 v99, v73, v122
	v_fmac_f32_e32 v99, v81, v124
	v_fmac_f32_e32 v99, v82, v125
	ds_read_b128 v[122:125], v87 offset:800
	v_add_f32_e32 v97, v97, v99
	s_waitcnt lgkmcnt(7)
	v_mul_f32_e32 v99, v70, v127
	v_fmac_f32_e32 v99, v67, v126
	v_fmac_f32_e32 v99, v76, v128
	v_fmac_f32_e32 v99, v74, v129
	ds_read_b128 v[126:129], v87 offset:816
	v_add_f32_e32 v97, v97, v99
	v_max_f32_e64 v98, -v97, 0
	v_mul_f32_e64 v97, |v97|, s64
	v_exp_f32_e32 v97, v97
	s_nop 0
	v_add_f32_e32 v97, 1.0, v97
	v_cmp_gt_f32_e32 vcc, s65, v97
	s_nop 1
	v_cndmask_b32_e64 v99, 0, 32, vcc
	v_ldexp_f32 v97, v97, v99
	v_log_f32_e32 v97, v97
	s_nop 0
	v_mul_f32_e32 v99, 0x3f317217, v97
	v_fma_f32 v99, v97, s66, -v99
	v_fmac_f32_e32 v99, 0x3377d1cf, v97
	v_fmac_f32_e32 v99, 0x3f317217, v97
	v_cmp_lt_f32_e64 s[40:41], |v97|, s67
	s_nop 1
	v_cndmask_b32_e64 v97, v97, v99, s[40:41]
	v_cndmask_b32_e32 v99, 0, v252, vcc
	v_sub_f32_e32 v97, v97, v99
	v_add_f32_e32 v97, v98, v97
	v_fmamk_f32 v97, v97, 0xbd800000, v96
	s_waitcnt lgkmcnt(7)
	v_mul_f32_e32 v99, v80, v131
	v_fmac_f32_e32 v99, v79, v130
	v_fmac_f32_e32 v99, v83, v132
	v_fmac_f32_e32 v99, v84, v133
	ds_read_b128 v[130:133], v87 offset:832
	v_add_f32_e32 v102, v85, v99
	s_waitcnt lgkmcnt(7)
	v_mul_f32_e32 v99, v72, v135
	v_fmac_f32_e32 v99, v71, v134
	v_fmac_f32_e32 v99, v77, v136
	v_fmac_f32_e32 v99, v78, v137
	ds_read_b128 v[134:137], v87 offset:848
	v_add_f32_e32 v102, v102, v99
	s_waitcnt lgkmcnt(7)
	v_mul_f32_e32 v99, v75, v139
	v_fmac_f32_e32 v99, v73, v138
	v_fmac_f32_e32 v99, v81, v140
	v_fmac_f32_e32 v99, v82, v141
	ds_read_b128 v[138:141], v87 offset:864
	v_add_f32_e32 v102, v102, v99
	s_waitcnt lgkmcnt(7)
	v_mul_f32_e32 v99, v70, v143
	v_fmac_f32_e32 v99, v67, v142
	v_fmac_f32_e32 v99, v76, v144
	v_fmac_f32_e32 v99, v74, v145
	ds_read_b128 v[142:145], v87 offset:880
	v_add_f32_e32 v98, v102, v99
	v_max_f32_e64 v99, -v98, 0
	v_mul_f32_e64 v98, |v98|, s64
	v_exp_f32_e32 v98, v98
	s_nop 0
	v_add_f32_e32 v98, 1.0, v98
	v_cmp_gt_f32_e32 vcc, s65, v98
	s_nop 1
	v_cndmask_b32_e64 v100, 0, 32, vcc
	v_ldexp_f32 v98, v98, v100
	v_log_f32_e32 v98, v98
	s_nop 0
	v_mul_f32_e32 v100, 0x3f317217, v98
	v_fma_f32 v100, v98, s66, -v100
	v_fmac_f32_e32 v100, 0x3377d1cf, v98
	v_fmac_f32_e32 v100, 0x3f317217, v98
	v_cmp_lt_f32_e64 s[40:41], |v98|, s67
	s_nop 1
	v_cndmask_b32_e64 v98, v98, v100, s[40:41]
	v_cndmask_b32_e32 v100, 0, v252, vcc
	v_sub_f32_e32 v98, v98, v100
	v_add_f32_e32 v98, v99, v98
	v_fmamk_f32 v98, v98, 0xbd800000, v97
	s_waitcnt lgkmcnt(7)
	v_mul_f32_e32 v99, v80, v115
	v_fmac_f32_e32 v99, v79, v114
	v_fmac_f32_e32 v99, v83, v116
	v_fmac_f32_e32 v99, v84, v117
	ds_read_b128 v[114:117], v87 offset:896
	v_add_f32_e32 v99, v85, v99
	s_waitcnt lgkmcnt(7)
	v_mul_f32_e32 v101, v72, v119
	v_fmac_f32_e32 v101, v71, v118
	v_fmac_f32_e32 v101, v77, v120
	v_fmac_f32_e32 v101, v78, v121
	ds_read_b128 v[118:121], v87 offset:912
	v_add_f32_e32 v99, v99, v101
	s_waitcnt lgkmcnt(7)
	v_mul_f32_e32 v101, v75, v123
	v_fmac_f32_e32 v101, v73, v122
	v_fmac_f32_e32 v101, v81, v124
	v_fmac_f32_e32 v101, v82, v125
	ds_read_b128 v[122:125], v87 offset:928
	v_add_f32_e32 v99, v99, v101
	s_waitcnt lgkmcnt(7)
	v_mul_f32_e32 v101, v70, v127
	v_fmac_f32_e32 v101, v67, v126
	v_fmac_f32_e32 v101, v76, v128
	v_fmac_f32_e32 v101, v74, v129
	ds_read_b128 v[126:129], v87 offset:944
	v_add_f32_e32 v99, v99, v101
	v_max_f32_e64 v100, -v99, 0
	v_mul_f32_e64 v99, |v99|, s64
	v_exp_f32_e32 v99, v99
	s_nop 0
	v_add_f32_e32 v99, 1.0, v99
	v_cmp_gt_f32_e32 vcc, s65, v99
	s_nop 1
	v_cndmask_b32_e64 v101, 0, 32, vcc
	v_ldexp_f32 v99, v99, v101
	v_log_f32_e32 v99, v99
	s_nop 0
	v_mul_f32_e32 v101, 0x3f317217, v99
	v_fma_f32 v101, v99, s66, -v101
	v_fmac_f32_e32 v101, 0x3377d1cf, v99
	v_fmac_f32_e32 v101, 0x3f317217, v99
	v_cmp_lt_f32_e64 s[40:41], |v99|, s67
	s_nop 1
	v_cndmask_b32_e64 v99, v99, v101, s[40:41]
	v_cndmask_b32_e32 v101, 0, v252, vcc
	v_sub_f32_e32 v99, v99, v101
	v_add_f32_e32 v99, v100, v99
	v_fmamk_f32 v99, v99, 0xbd800000, v98
	s_waitcnt lgkmcnt(7)
	v_mul_f32_e32 v101, v80, v131
	v_fmac_f32_e32 v101, v79, v130
	v_fmac_f32_e32 v101, v83, v132
	v_fmac_f32_e32 v101, v84, v133
	ds_read_b128 v[130:133], v87 offset:960
	v_add_f32_e32 v104, v85, v101
	s_waitcnt lgkmcnt(7)
	v_mul_f32_e32 v101, v72, v135
	v_fmac_f32_e32 v101, v71, v134
	v_fmac_f32_e32 v101, v77, v136
	v_fmac_f32_e32 v101, v78, v137
	ds_read_b128 v[134:137], v87 offset:976
	v_add_f32_e32 v104, v104, v101
	s_waitcnt lgkmcnt(7)
	v_mul_f32_e32 v101, v75, v139
	v_fmac_f32_e32 v101, v73, v138
	v_fmac_f32_e32 v101, v81, v140
	v_fmac_f32_e32 v101, v82, v141
	ds_read_b128 v[138:141], v87 offset:992
	v_add_f32_e32 v104, v104, v101
	s_waitcnt lgkmcnt(7)
	v_mul_f32_e32 v101, v70, v143
	v_fmac_f32_e32 v101, v67, v142
	v_fmac_f32_e32 v101, v76, v144
	v_fmac_f32_e32 v101, v74, v145
	ds_read_b128 v[142:145], v87 offset:1008
	v_add_f32_e32 v100, v104, v101
	v_max_f32_e64 v101, -v100, 0
	v_mul_f32_e64 v100, |v100|, s64
	v_exp_f32_e32 v100, v100
	s_nop 0
	v_add_f32_e32 v100, 1.0, v100
	v_cmp_gt_f32_e32 vcc, s65, v100
	s_nop 1
	v_cndmask_b32_e64 v102, 0, 32, vcc
	v_ldexp_f32 v100, v100, v102
	v_log_f32_e32 v100, v100
	s_nop 0
	v_mul_f32_e32 v102, 0x3f317217, v100
	v_fma_f32 v102, v100, s66, -v102
	v_fmac_f32_e32 v102, 0x3377d1cf, v100
	v_fmac_f32_e32 v102, 0x3f317217, v100
	v_cmp_lt_f32_e64 s[40:41], |v100|, s67
	s_nop 1
	v_cndmask_b32_e64 v100, v100, v102, s[40:41]
	v_cndmask_b32_e32 v102, 0, v252, vcc
	v_sub_f32_e32 v100, v100, v102
	v_add_f32_e32 v100, v101, v100
	v_fmamk_f32 v100, v100, 0xbd800000, v99
	s_waitcnt lgkmcnt(7)
; #define LAS __attribute__((address_space(3)))
; __device__ __forceinline__ float bf2f(unsigned short h) { return __uint_as_float((unsigned)h << 16); }
; __device__ __forceinline__ unsigned short f2bf(float f) { return (unsigned short)(pg8::cvt_pk_bf16(f, 0.f) & 0xffffu); }
; __device__ __forceinline__ void gla_logdecay(float (&b)[16], float& blast, const LAS float* glrs, const float (&wcol)[16], const float bias, int d, int g, LAS float* tot) {
;     ...
;     for (int ii = 0; ii < 16; ++ii) { const LAS f32x4* gr = (const LAS f32x4*)(glrs + (16 * g + ii) * 16); float z = bias;
; #pragma unroll
;         for (int r4 = 0; r4 < 4; ++r4) { const f32x4 gv = gr[r4]; z += gv[0] * wcol[4 * r4] + gv[1] * wcol[4 * r4 + 1] + gv[2] * wcol[4 * r4 + 2] + gv[3] * wcol[4 * r4 + 3]; }
;         const float la = -(fmaxf(-z, 0.f) + __logf(1.0f + __expf(-fabsf(z)))) * (1.0f / 16.0f);
;         run += la; b[ii] = run; }
;     tot[g * 128 + d] = run;
;     __syncthreads();
;     float off = 0.f, all = 0.f;
; #pragma unroll
;     for (int gg = 0; gg < 4; ++gg) { const float tv = tot[gg * 128 + d]; all += tv; if (gg < g) off += tv; }
; #pragma unroll
;     for (int ii = 0; ii < 16; ++ii) b[ii] += off;
;     blast = all;
; __device__ __forceinline__ void gla_stepC(LAS unsigned char* lds, int item, const bf16* proj, const bf16* vtg, const float* glr, const float* W2, const float* b2, const bf16* sT, const float* gout, bf16* mix) {
;     ...
;       for (int ii = 0; ii < 16; ++ii) { const float eb = __expf(b[ii]); const int o_ = (16 * g + ii) * QP + d;
;           QE[o_] = f2bf(bf2f(QE[o_]) * 0.08838834764831845f * eb);
;           KE[o_] = f2bf(bf2f(KE[o_]) * __builtin_amdgcn_rcpf(eb)); } }
	v_mul_f32_e32 v101, v80, v115
	v_fmac_f32_e32 v101, v79, v114
	v_fmac_f32_e32 v101, v83, v116
	v_fmac_f32_e32 v101, v84, v117
	v_add_f32_e32 v101, v85, v101
	s_waitcnt lgkmcnt(6)
	v_mul_f32_e32 v103, v72, v119
	v_fmac_f32_e32 v103, v71, v118
	v_fmac_f32_e32 v103, v77, v120
	v_fmac_f32_e32 v103, v78, v121
	v_add_f32_e32 v101, v101, v103
	s_waitcnt lgkmcnt(5)
	v_mul_f32_e32 v103, v75, v123
	v_fmac_f32_e32 v103, v73, v122
	v_fmac_f32_e32 v103, v81, v124
	v_fmac_f32_e32 v103, v82, v125
	v_add_f32_e32 v101, v101, v103
	s_waitcnt lgkmcnt(4)
	v_mul_f32_e32 v103, v70, v127
	v_fmac_f32_e32 v103, v67, v126
	v_fmac_f32_e32 v103, v76, v128
	v_fmac_f32_e32 v103, v74, v129
	v_add_f32_e32 v101, v101, v103
	v_max_f32_e64 v102, -v101, 0
	v_mul_f32_e64 v101, |v101|, s64
	v_exp_f32_e32 v101, v101
	s_nop 0
	v_add_f32_e32 v101, 1.0, v101
	v_cmp_gt_f32_e32 vcc, s65, v101
	s_nop 1
	v_cndmask_b32_e64 v103, 0, 32, vcc
	v_ldexp_f32 v101, v101, v103
	v_log_f32_e32 v101, v101
	s_nop 0
	v_mul_f32_e32 v103, 0x3f317217, v101
	v_fma_f32 v103, v101, s66, -v103
	v_fmac_f32_e32 v103, 0x3377d1cf, v101
	v_fmac_f32_e32 v103, 0x3f317217, v101
	v_cmp_lt_f32_e64 s[40:41], |v101|, s67
	s_nop 1
	v_cndmask_b32_e64 v101, v101, v103, s[40:41]
	v_cndmask_b32_e32 v103, 0, v252, vcc
	v_sub_f32_e32 v101, v101, v103
	v_add_f32_e32 v101, v102, v101
	v_fmamk_f32 v101, v101, 0xbd800000, v100
	s_waitcnt lgkmcnt(3)
	v_mul_f32_e32 v80, v80, v131
	v_fmac_f32_e32 v80, v79, v130
	v_fmac_f32_e32 v80, v83, v132
	v_fmac_f32_e32 v80, v84, v133
	v_add_f32_e32 v79, v85, v80
	s_waitcnt lgkmcnt(2)
	v_mul_f32_e32 v72, v72, v135
	v_fmac_f32_e32 v72, v71, v134
	v_fmac_f32_e32 v72, v77, v136
	v_fmac_f32_e32 v72, v78, v137
	v_add_f32_e32 v71, v79, v72
	s_waitcnt lgkmcnt(1)
	v_mul_f32_e32 v72, v75, v139
	v_fmac_f32_e32 v72, v73, v138
	v_fmac_f32_e32 v72, v81, v140
	v_fmac_f32_e32 v72, v82, v141
	v_add_f32_e32 v71, v71, v72
	s_waitcnt lgkmcnt(0)
	v_mul_f32_e32 v70, v70, v143
	v_fmac_f32_e32 v70, v67, v142
	v_fmac_f32_e32 v70, v76, v144
	v_fmac_f32_e32 v70, v74, v145
	v_add_f32_e32 v67, v71, v70
	v_max_f32_e64 v70, -v67, 0
	v_mul_f32_e64 v67, |v67|, s64
	v_exp_f32_e32 v67, v67
	s_nop 0
	v_add_f32_e32 v67, 1.0, v67
	v_cmp_gt_f32_e32 vcc, s65, v67
	s_nop 1
	v_cndmask_b32_e64 v71, 0, 32, vcc
	v_ldexp_f32 v67, v67, v71
	v_log_f32_e32 v67, v67
	s_nop 0
	v_mul_f32_e32 v71, 0x3f317217, v67
	v_fma_f32 v71, v67, s66, -v71
	v_fmac_f32_e32 v71, 0x3377d1cf, v67
	v_fmac_f32_e32 v71, 0x3f317217, v67
	v_cmp_lt_f32_e64 s[40:41], |v67|, s67
	s_nop 1
	v_cndmask_b32_e64 v67, v67, v71, s[40:41]
	v_cndmask_b32_e32 v71, 0, v252, vcc
	v_sub_f32_e32 v67, v67, v71
	v_add_f32_e32 v67, v70, v67
	v_lshl_add_u32 v70, v43, 2, 0
	v_add_u32_e32 v72, 0x14400, v70
	v_fmamk_f32 v67, v67, 0xbd800000, v101
	v_lshl_add_u32 v70, v41, 9, v72
	ds_write_b32 v70, v67
	s_waitcnt lgkmcnt(0)
	s_barrier
	ds_read2st64_b32 v[114:115], v72 offset1:2
	ds_read2st64_b32 v[118:119], v72 offset0:4 offset1:6
	v_cmp_lt_i32_e32 vcc, 0, v41
	s_waitcnt lgkmcnt(1)
	v_add_f32_e32 v70, 0, v114
	v_cndmask_b32_e32 v70, 0, v70, vcc
	v_cmp_lt_i32_e32 vcc, 1, v41
	v_add_f32_e32 v71, v115, v70
	s_nop 0
	v_cndmask_b32_e32 v73, v70, v71, vcc
	v_cmp_lt_i32_e32 vcc, 2, v41
	s_waitcnt lgkmcnt(0)
	v_add_f32_e32 v70, v118, v73
	v_cndmask_b32_e32 v70, v73, v70, vcc
	v_cmp_lt_i32_e32 vcc, 3, v41
	v_add_f32_e32 v71, v119, v70
	s_nop 0
	v_cndmask_b32_e32 v77, v70, v71, vcc
	v_add_f32_e32 v78, v86, v77
	v_add_f32_e32 v79, v88, v77
	v_add_f32_e32 v80, v89, v77
	v_add_f32_e32 v81, v90, v77
	v_add_f32_e32 v82, v91, v77
	v_add_f32_e32 v83, v92, v77
	v_add_f32_e32 v84, v93, v77
	v_add_f32_e32 v85, v94, v77
	v_add_f32_e32 v76, v95, v77
	v_add_f32_e32 v75, v96, v77
	v_add_f32_e32 v74, v97, v77
	v_add_f32_e32 v73, v98, v77
	v_add_f32_e32 v72, v99, v77
	v_add_f32_e32 v71, v100, v77
	v_add_f32_e32 v70, v101, v77
	v_add_f32_e32 v67, v77, v67
	v_mul_f32_e32 v77, 0x3fb8aa3b, v78
	v_mul_lo_u32 v78, v41, s0
	v_or_b32_e32 v43, v78, v43
	v_lshl_add_u32 v43, v43, 1, 0
	ds_read_u16 v122, v43
	ds_read_u16 v126, v43 offset:18432
	ds_read_u16 v130, v43 offset:288
	ds_read_u16 v134, v43 offset:18720
	ds_read_u16 v138, v43 offset:576
	ds_read_u16 v142, v43 offset:19008
	ds_read_u16 v146, v43 offset:864
	ds_read_u16 v114, v43 offset:19296
	ds_read_u16 v118, v43 offset:1152
	v_exp_f32_e32 v77, v77
	v_mul_f32_e32 v76, 0x3fb8aa3b, v76
	v_exp_f32_e32 v76, v76
	v_mul_f32_e32 v75, 0x3fb8aa3b, v75
	s_waitcnt lgkmcnt(8)
	v_lshlrev_b32_e32 v78, 16, v122
	ds_read_u16 v122, v43 offset:19584
	v_mul_f32_e32 v78, 0x3db504f3, v78
	v_mul_f32_e32 v78, v78, v77
	v_cvt_pk_bf16_f32 v78, v78, v153
	ds_write_b16 v43, v78
	v_rcp_f32_e32 v77, v77
	v_exp_f32_e32 v75, v75
	v_mul_f32_e32 v74, 0x3fb8aa3b, v74
	v_exp_f32_e32 v74, v74
	s_waitcnt lgkmcnt(9)
	v_lshlrev_b32_e32 v78, 16, v126
	ds_read_u16 v126, v43 offset:1440
	v_mul_f32_e32 v77, v77, v78
	v_cvt_pk_bf16_f32 v77, v77, v153
	ds_write_b16 v43, v77 offset:18432
	v_mul_f32_e32 v77, 0x3fb8aa3b, v79
	v_exp_f32_e32 v77, v77
	v_mul_f32_e32 v73, 0x3fb8aa3b, v73
	s_waitcnt lgkmcnt(10)
	v_lshlrev_b32_e32 v78, 16, v130
	ds_read_u16 v130, v43 offset:19872
	v_mul_f32_e32 v78, 0x3db504f3, v78
	v_mul_f32_e32 v78, v77, v78
	v_cvt_pk_bf16_f32 v78, v78, v153
	ds_write_b16 v43, v78 offset:288
	v_rcp_f32_e32 v77, v77
	v_exp_f32_e32 v73, v73
	v_mul_f32_e32 v72, 0x3fb8aa3b, v72
	v_exp_f32_e32 v72, v72
	s_waitcnt lgkmcnt(11)
	v_lshlrev_b32_e32 v78, 16, v134
	ds_read_u16 v134, v43 offset:1728
	v_mul_f32_e32 v77, v77, v78
	v_cvt_pk_bf16_f32 v77, v77, v153
	ds_write_b16 v43, v77 offset:18720
	v_mul_f32_e32 v77, 0x3fb8aa3b, v80
	v_exp_f32_e32 v77, v77
	v_mul_f32_e32 v71, 0x3fb8aa3b, v71
	s_waitcnt lgkmcnt(12)
; __device__ __forceinline__ float bf2f(unsigned short h) { return __uint_as_float((unsigned)h << 16); }
; __device__ __forceinline__ unsigned short f2bf(float f) { return (unsigned short)(pg8::cvt_pk_bf16(f, 0.f) & 0xffffu); }
; __device__ __forceinline__ void gla_stepC(LAS unsigned char* lds, int item, const bf16* proj, const bf16* vtg, const float* glr, const float* W2, const float* b2, const bf16* sT, const float* gout, bf16* mix) {
;     ...
;       for (int ii = 0; ii < 16; ++ii) { const float eb = __expf(b[ii]); const int o_ = (16 * g + ii) * QP + d;
;           QE[o_] = f2bf(bf2f(QE[o_]) * 0.08838834764831845f * eb);
;           KE[o_] = f2bf(bf2f(KE[o_]) * __builtin_amdgcn_rcpf(eb)); } }
;     __syncthreads();
	v_lshlrev_b32_e32 v78, 16, v138
	ds_read_u16 v138, v43 offset:20160
	v_mul_f32_e32 v78, 0x3db504f3, v78
	v_mul_f32_e32 v78, v77, v78
	v_cvt_pk_bf16_f32 v78, v78, v153
	ds_write_b16 v43, v78 offset:576
	v_rcp_f32_e32 v77, v77
	v_exp_f32_e32 v71, v71
	v_mul_f32_e32 v70, 0x3fb8aa3b, v70
	v_exp_f32_e32 v70, v70
	s_waitcnt lgkmcnt(13)
	v_lshlrev_b32_e32 v78, 16, v142
	ds_read_u16 v142, v43 offset:2016
	v_mul_f32_e32 v77, v77, v78
	v_cvt_pk_bf16_f32 v77, v77, v153
	ds_write_b16 v43, v77 offset:19008
	v_mul_f32_e32 v77, 0x3fb8aa3b, v81
	v_exp_f32_e32 v77, v77
	v_mul_f32_e32 v67, 0x3fb8aa3b, v67
	s_waitcnt lgkmcnt(14)
	v_lshlrev_b32_e32 v78, 16, v146
	v_mul_f32_e32 v78, 0x3db504f3, v78
	v_mul_f32_e32 v78, v77, v78
	v_cvt_pk_bf16_f32 v78, v78, v153
	ds_write_b16 v43, v78 offset:864
	v_rcp_f32_e32 v77, v77
	v_exp_f32_e32 v67, v67
	v_lshl_or_b32 v41, v41, 4, v47
	v_readlane_b32 s0, v255, 14
	s_waitcnt lgkmcnt(14)
	v_lshlrev_b32_e32 v78, 16, v114
	v_mul_f32_e32 v77, v77, v78
	v_cvt_pk_bf16_f32 v77, v77, v153
	ds_write_b16 v43, v77 offset:19296
	v_mul_f32_e32 v77, 0x3fb8aa3b, v82
	v_exp_f32_e32 v77, v77
	s_waitcnt lgkmcnt(14)
	v_lshlrev_b32_e32 v78, 16, v118
	v_mul_f32_e32 v78, 0x3db504f3, v78
	v_mul_f32_e32 v78, v77, v78
	v_cvt_pk_bf16_f32 v78, v78, v153
	ds_write_b16 v43, v78 offset:1152
	v_rcp_f32_e32 v77, v77
	s_waitcnt lgkmcnt(14)
	v_lshlrev_b32_e32 v78, 16, v122
	v_mul_f32_e32 v77, v77, v78
	v_cvt_pk_bf16_f32 v77, v77, v153
	ds_write_b16 v43, v77 offset:19584
	v_mul_f32_e32 v77, 0x3fb8aa3b, v83
	v_exp_f32_e32 v77, v77
	s_waitcnt lgkmcnt(13)
	v_lshlrev_b32_e32 v78, 16, v126
	ds_read_u16 v146, v43 offset:20448
	v_mul_f32_e32 v78, 0x3db504f3, v78
	v_mul_f32_e32 v78, v77, v78
	v_cvt_pk_bf16_f32 v78, v78, v153
	ds_write_b16 v43, v78 offset:1440
	v_rcp_f32_e32 v77, v77
	s_waitcnt lgkmcnt(13)
	v_lshlrev_b32_e32 v78, 16, v130
	ds_read_u16 v114, v43 offset:2304
	v_mul_f32_e32 v77, v77, v78
	v_cvt_pk_bf16_f32 v77, v77, v153
	ds_write_b16 v43, v77 offset:19872
	v_mul_f32_e32 v77, 0x3fb8aa3b, v84
	v_exp_f32_e32 v77, v77
	s_waitcnt lgkmcnt(13)
	v_lshlrev_b32_e32 v78, 16, v134
	ds_read_u16 v118, v43 offset:20736
	v_mul_f32_e32 v78, 0x3db504f3, v78
	v_mul_f32_e32 v78, v77, v78
	v_cvt_pk_bf16_f32 v78, v78, v153
	ds_write_b16 v43, v78 offset:1728
	v_rcp_f32_e32 v77, v77
	s_waitcnt lgkmcnt(13)
	v_lshlrev_b32_e32 v78, 16, v138
	ds_read_u16 v122, v43 offset:2592
	v_mul_f32_e32 v77, v77, v78
	v_cvt_pk_bf16_f32 v77, v77, v153
	ds_write_b16 v43, v77 offset:20160
	v_mul_f32_e32 v77, 0x3fb8aa3b, v85
	v_exp_f32_e32 v77, v77
	s_waitcnt lgkmcnt(13)
	v_lshlrev_b32_e32 v78, 16, v142
	ds_read_u16 v126, v43 offset:21024
	v_mul_f32_e32 v78, 0x3db504f3, v78
	v_mul_f32_e32 v78, v77, v78
	v_cvt_pk_bf16_f32 v78, v78, v153
	ds_write_b16 v43, v78 offset:2016
	v_rcp_f32_e32 v77, v77
	s_waitcnt lgkmcnt(9)
	v_lshlrev_b32_e32 v78, 16, v146
	ds_read_u16 v130, v43 offset:2880
	ds_read_u16 v134, v43 offset:21312
	ds_read_u16 v138, v43 offset:3168
	ds_read_u16 v142, v43 offset:21600
	ds_read_u16 v146, v43 offset:3456
	v_mul_f32_e32 v77, v77, v78
	v_cvt_pk_bf16_f32 v77, v77, v153
	ds_write_b16 v43, v77 offset:20448
	s_waitcnt lgkmcnt(13)
	v_lshlrev_b32_e32 v77, 16, v114
	ds_read_u16 v114, v43 offset:21888
	v_mul_f32_e32 v77, 0x3db504f3, v77
	v_mul_f32_e32 v77, v76, v77
	v_cvt_pk_bf16_f32 v77, v77, v153
	ds_write_b16 v43, v77 offset:2304
	v_rcp_f32_e32 v76, v76
	s_waitcnt lgkmcnt(13)
	v_lshlrev_b32_e32 v77, 16, v118
	ds_read_u16 v118, v43 offset:3744
	v_mul_f32_e32 v76, v76, v77
	v_cvt_pk_bf16_f32 v76, v76, v153
	ds_write_b16 v43, v76 offset:20736
	s_waitcnt lgkmcnt(13)
	v_lshlrev_b32_e32 v76, 16, v122
	ds_read_u16 v122, v43 offset:22176
	v_mul_f32_e32 v76, 0x3db504f3, v76
	v_mul_f32_e32 v76, v75, v76
	v_cvt_pk_bf16_f32 v76, v76, v153
	ds_write_b16 v43, v76 offset:2592
	v_rcp_f32_e32 v75, v75
	s_waitcnt lgkmcnt(13)
	v_lshlrev_b32_e32 v76, 16, v126
	ds_read_u16 v126, v43 offset:4032
	v_mul_f32_e32 v75, v75, v76
	v_cvt_pk_bf16_f32 v75, v75, v153
	ds_write_b16 v43, v75 offset:21024
	s_waitcnt lgkmcnt(13)
	v_lshlrev_b32_e32 v75, 16, v130
	ds_read_u16 v130, v43 offset:22464
	v_mul_f32_e32 v75, 0x3db504f3, v75
	v_mul_f32_e32 v75, v74, v75
	v_cvt_pk_bf16_f32 v75, v75, v153
	ds_write_b16 v43, v75 offset:2880
	v_rcp_f32_e32 v74, v74
	s_waitcnt lgkmcnt(14)
	v_lshlrev_b32_e32 v75, 16, v134
	v_mul_f32_e32 v74, v74, v75
	v_cvt_pk_bf16_f32 v74, v74, v153
	ds_write_b16 v43, v74 offset:21312
	s_waitcnt lgkmcnt(14)
	v_lshlrev_b32_e32 v74, 16, v138
	v_mul_f32_e32 v74, 0x3db504f3, v74
	v_mul_f32_e32 v74, v73, v74
	v_cvt_pk_bf16_f32 v74, v74, v153
	ds_write_b16 v43, v74 offset:3168
	v_rcp_f32_e32 v73, v73
	s_waitcnt lgkmcnt(14)
	v_lshlrev_b32_e32 v74, 16, v142
	v_mul_f32_e32 v73, v73, v74
	v_cvt_pk_bf16_f32 v73, v73, v153
	ds_write_b16 v43, v73 offset:21600
	s_waitcnt lgkmcnt(14)
	v_lshlrev_b32_e32 v73, 16, v146
	v_mul_f32_e32 v73, 0x3db504f3, v73
	v_mul_f32_e32 v73, v72, v73
	v_cvt_pk_bf16_f32 v73, v73, v153
	ds_write_b16 v43, v73 offset:3456
	v_rcp_f32_e32 v72, v72
	s_waitcnt lgkmcnt(13)
	v_lshlrev_b32_e32 v73, 16, v114
	ds_read_u16 v134, v43 offset:4320
	v_mul_f32_e32 v72, v72, v73
	v_cvt_pk_bf16_f32 v72, v72, v153
	ds_write_b16 v43, v72 offset:21888
	s_waitcnt lgkmcnt(13)
	v_lshlrev_b32_e32 v72, 16, v118
	ds_read_u16 v138, v43 offset:22752
	v_mul_f32_e32 v72, 0x3db504f3, v72
	v_mul_f32_e32 v72, v71, v72
	v_cvt_pk_bf16_f32 v72, v72, v153
	ds_write_b16 v43, v72 offset:3744
	v_rcp_f32_e32 v71, v71
	s_waitcnt lgkmcnt(13)
	v_lshlrev_b32_e32 v72, 16, v122
	v_mul_f32_e32 v71, v71, v72
	v_cvt_pk_bf16_f32 v71, v71, v153
	ds_write_b16 v43, v71 offset:22176
	s_waitcnt lgkmcnt(12)
	v_lshlrev_b32_e32 v71, 16, v126
	v_mul_f32_e32 v71, 0x3db504f3, v71
	v_mul_f32_e32 v71, v70, v71
	v_cvt_pk_bf16_f32 v71, v71, v153
	ds_write_b16 v43, v71 offset:4032
	v_rcp_f32_e32 v70, v70
	s_waitcnt lgkmcnt(11)
	v_lshlrev_b32_e32 v71, 16, v130
	v_mul_f32_e32 v70, v70, v71
	v_cvt_pk_bf16_f32 v70, v70, v153
	ds_write_b16 v43, v70 offset:22464
	s_waitcnt lgkmcnt(6)
	v_lshlrev_b32_e32 v70, 16, v134
	v_mul_f32_e32 v70, 0x3db504f3, v70
	v_mul_f32_e32 v70, v67, v70
	v_cvt_pk_bf16_f32 v70, v70, v153
	ds_write_b16 v43, v70 offset:4320
	v_rcp_f32_e32 v67, v67
	s_waitcnt lgkmcnt(5)
	v_lshlrev_b32_e32 v70, 16, v138
	v_mul_f32_e32 v67, v67, v70
	v_cvt_pk_bf16_f32 v67, v67, v153
	ds_write_b16 v43, v67 offset:22752
	v_and_b32_e32 v43, 32, v42
	v_add_u32_e32 v42, 0, v152
	v_mad_u64_u32 v[82:83], s[14:15], v41, s94, v[42:43]
	v_or_b32_e32 v70, v43, v47
	v_mad_u32_u24 v83, v70, s94, v42
	s_waitcnt lgkmcnt(0)
	s_barrier
; #define LAS __attribute__((address_space(3)))
; __device__ __forceinline__ unsigned pk2(float lo, float hi) { return pg8::cvt_pk_bf16(lo, hi); }
; #define MMA16(X, Y, ACC) ACC = __builtin_amdgcn_mfma_f32_16x16x32_bf16((X), (Y), (ACC), 0, 0, 0)
; __device__ __forceinline__ void gla_stepC(LAS unsigned char* lds, int item, const bf16* proj, const bf16* vtg, const float* glr, const float* W2, const float* b2, const bf16* sT, const float* gout, bf16* mix) {
;     ...
;     { const int ib = w >> 1;
; #pragma unroll
;       for (int jj = 0; jj < 2; ++jj) { const int jb = 2 * (w & 1) + jj; f32x4 a = (f32x4){0.f, 0.f, 0.f, 0.f};
; #pragma unroll
;           for (int ks = 0; ks < 4; ++ks) { const bf16x8 kf = *(const LAS bf16x8*)(KE + (16 * jb + fr) * QP + 32 * ks + 8 * fq); const bf16x8 qf = *(const LAS bf16x8*)(QE + (16 * ib + fr) * QP + 32 * ks + 8 * fq); MMA16(kf, qf, a); }
;           const int i = 16 * ib + fr, j0 = 16 * jb + 4 * fq;
;           u32x2 ov; ov.x = pk2(j0 <= i ? a[0] : 0.f, j0 + 1 <= i ? a[1] : 0.f); ov.y = pk2(j0 + 2 <= i ? a[2] : 0.f, j0 + 3 <= i ? a[3] : 0.f);
;           *(LAS u32x2*)(AS + i * VP + j0) = ov; } }
;     __syncthreads();
	ds_read_b128 v[114:117], v83 offset:18432
	ds_read_b128 v[118:121], v82
	ds_read_b128 v[122:125], v83 offset:18496
	ds_read_b128 v[126:129], v82 offset:64
	ds_read_b128 v[130:133], v83 offset:18560
	ds_read_b128 v[134:137], v82 offset:128
	ds_read_b128 v[138:141], v83 offset:18624
	ds_read_b128 v[142:145], v82 offset:192
	s_waitcnt lgkmcnt(6)
	v_mfma_f32_16x16x32_bf16 v[70:73], v[114:117], v[118:121], 0
	v_mul_lo_u32 v67, v41, s16
	s_waitcnt lgkmcnt(4)
	v_mfma_f32_16x16x32_bf16 v[70:73], v[122:125], v[126:129], v[70:73]
	s_waitcnt lgkmcnt(2)
	v_mfma_f32_16x16x32_bf16 v[70:73], v[130:133], v[134:137], v[70:73]
	s_waitcnt lgkmcnt(0)
	v_mfma_f32_16x16x32_bf16 v[70:73], v[138:141], v[142:145], v[70:73]
	v_or_b32_e32 v74, v43, v63
	v_cmp_le_i32_e32 vcc, v74, v41
	v_or_b32_e32 v43, 16, v43
	s_nop 4
	v_cndmask_b32_e32 v70, 0, v70, vcc
	v_cmp_lt_i32_e32 vcc, v74, v41
	s_nop 1
	v_cndmask_b32_e32 v71, 0, v71, vcc
	v_cvt_pk_bf16_f32 v70, v70, v71
	v_or_b32_e32 v71, 2, v74
	v_cmp_le_i32_e32 vcc, v71, v41
	s_nop 1
	v_cndmask_b32_e32 v71, 0, v72, vcc
	v_or_b32_e32 v72, 3, v74
	v_cmp_le_i32_e32 vcc, v72, v41
	s_nop 1
	v_cndmask_b32_e32 v72, 0, v73, vcc
	v_cvt_pk_bf16_f32 v71, v71, v72
	v_lshlrev_b32_e32 v72, 1, v74
	v_add3_u32 v67, s0, v67, v72
	ds_write_b64 v67, v[70:71]
	v_or_b32_e32 v70, v43, v47
	v_mad_u32_u24 v83, v70, s94, v42
	ds_read_b128 v[146:149], v83 offset:18432
	ds_read_b128 v[114:117], v82
	ds_read_b128 v[118:121], v83 offset:18496
	ds_read_b128 v[122:125], v82 offset:64
	ds_read_b128 v[126:129], v83 offset:18560
	ds_read_b128 v[130:133], v82 offset:128
	ds_read_b128 v[134:137], v83 offset:18624
	ds_read_b128 v[138:141], v82 offset:192
	s_waitcnt lgkmcnt(6)
	v_mfma_f32_16x16x32_bf16 v[70:73], v[146:149], v[114:117], 0
	v_or_b32_e32 v43, v43, v63
	v_cmp_le_i32_e32 vcc, v43, v41
	s_waitcnt lgkmcnt(4)
	v_mfma_f32_16x16x32_bf16 v[70:73], v[118:121], v[122:125], v[70:73]
	s_waitcnt lgkmcnt(2)
	v_mfma_f32_16x16x32_bf16 v[70:73], v[126:129], v[130:133], v[70:73]
	s_waitcnt lgkmcnt(0)
	v_mfma_f32_16x16x32_bf16 v[70:73], v[134:137], v[138:141], v[70:73]
	s_nop 7
	v_cndmask_b32_e32 v70, 0, v70, vcc
	v_cmp_lt_i32_e32 vcc, v43, v41
	s_nop 1
	v_cndmask_b32_e32 v71, 0, v71, vcc
	v_cvt_pk_bf16_f32 v70, v70, v71
	v_or_b32_e32 v71, 2, v43
	v_cmp_le_i32_e32 vcc, v71, v41
	v_or_b32_e32 v43, 3, v43
	s_nop 0
	v_cndmask_b32_e32 v71, 0, v72, vcc
	v_cmp_le_i32_e32 vcc, v43, v41
	s_nop 1
	v_cndmask_b32_e32 v41, 0, v73, vcc
	v_cvt_pk_bf16_f32 v71, v71, v41
	v_mad_u64_u32 v[40:41], s[14:15], v40, s16, v[42:43]
	v_mul_u32_u24_e32 v41, 0x90, v47
	v_add3_u32 v41, s0, v152, v41
	ds_write_b64 v67, v[70:71] offset:32
	s_waitcnt lgkmcnt(0)
	s_barrier
; #define LAS __attribute__((address_space(3)))
; #define MMA16(X, Y, ACC) ACC = __builtin_amdgcn_mfma_f32_16x16x32_bf16((X), (Y), (ACC), 0, 0, 0)
; __device__ __forceinline__ void gla_stepC(LAS unsigned char* lds, int item, const bf16* proj, const bf16* vtg, const float* glr, const float* W2, const float* b2, const bf16* sT, const float* gout, bf16* mix) {
;     ...
;     f32x4 acc[2][4];
; #pragma unroll
;     for (int eb = 0; eb < 2; ++eb)
; #pragma unroll
;         for (int ib = 0; ib < 4; ++ib) acc[eb][ib] = (f32x4){0.f, 0.f, 0.f, 0.f};
; #pragma unroll
;     for (int ks = 0; ks < 2; ++ks) { bf16x8 vf[2];
; #pragma unroll
;         for (int eb = 0; eb < 2; ++eb) vf[eb] = *(const LAS bf16x8*)(VT + (32 * w + 16 * eb + fr) * VP + 32 * ks + 8 * fq);
; #pragma unroll
;         for (int ib = 0; ib < 4; ++ib) { const bf16x8 af = *(const LAS bf16x8*)(AS + (16 * ib + fr) * VP + 32 * ks + 8 * fq);
; #pragma unroll
;             for (int eb = 0; eb < 2; ++eb) MMA16(vf[eb], af, acc[eb][ib]); } }
; #pragma unroll
;     for (int ks = 0; ks < 4; ++ks) {
; #pragma unroll
;         for (int ib = 0; ib < 4; ++ib) { const bf16x8 qf = *(const LAS bf16x8*)(QE + (16 * ib + fr) * QP + 32 * ks + 8 * fq);
; #pragma unroll
;             for (int eb = 0; eb < 2; ++eb) MMA16(sfr[ks][eb], qf, acc[eb][ib]); } }
; #pragma unroll
	ds_read_b128 v[114:117], v40 offset:36864
	ds_read_b128 v[118:121], v40 offset:39168
	ds_read_b128 v[122:125], v41
	ds_read_b128 v[126:129], v41 offset:2304
	ds_read_b128 v[130:133], v41 offset:4608
	ds_read_b128 v[134:137], v41 offset:6912
	ds_read_b128 v[138:141], v40 offset:36928
	ds_read_b128 v[142:145], v40 offset:39232
	ds_read_b128 v[146:149], v41 offset:64
	s_waitcnt lgkmcnt(6)
	v_mfma_f32_16x16x32_bf16 v[82:85], v[114:117], v[122:125], 0
	v_mad_u32_u24 v67, v47, s94, v42
	v_cmp_lt_i32_e32 vcc, v179, v180
	v_readlane_b32 s0, v255, 18
	s_waitcnt lgkmcnt(7)
	v_mfma_f32_16x16x32_bf16 v[78:81], v[118:121], v[122:125], 0
	ds_read_b128 v[122:125], v41 offset:2368
	s_waitcnt lgkmcnt(6)
	v_mfma_f32_16x16x32_bf16 v[90:93], v[114:117], v[126:129], 0
	v_mfma_f32_16x16x32_bf16 v[86:89], v[118:121], v[126:129], 0
	ds_read_b128 v[126:129], v41 offset:4672
	s_waitcnt lgkmcnt(6)
	v_mfma_f32_16x16x32_bf16 v[98:101], v[114:117], v[130:133], 0
	v_mfma_f32_16x16x32_bf16 v[94:97], v[118:121], v[130:133], 0
	ds_read_b128 v[130:133], v41 offset:6976
	s_waitcnt lgkmcnt(6)
	v_mfma_f32_16x16x32_bf16 v[70:73], v[114:117], v[134:137], 0
	ds_read_b128 v[114:117], v67
	v_mfma_f32_16x16x32_bf16 v[74:77], v[118:121], v[134:137], 0
	ds_read_b128 v[118:121], v67 offset:4608
	ds_read_b128 v[134:137], v67 offset:9216
	s_waitcnt lgkmcnt(6)
	v_mfma_f32_16x16x32_bf16 v[82:85], v[138:141], v[146:149], v[82:85]
	s_waitcnt lgkmcnt(7)
	v_mfma_f32_16x16x32_bf16 v[78:81], v[142:145], v[146:149], v[78:81]
	ds_read_b128 v[146:149], v67 offset:13824
	s_waitcnt lgkmcnt(6)
	v_mfma_f32_16x16x32_bf16 v[90:93], v[138:141], v[122:125], v[90:93]
	v_mfma_f32_16x16x32_bf16 v[86:89], v[142:145], v[122:125], v[86:89]
	ds_read_b128 v[122:125], v67 offset:64
	s_waitcnt lgkmcnt(6)
	v_mfma_f32_16x16x32_bf16 v[98:101], v[138:141], v[126:129], v[98:101]
	v_mfma_f32_16x16x32_bf16 v[94:97], v[142:145], v[126:129], v[94:97]
	ds_read_b128 v[126:129], v67 offset:4672
	s_waitcnt lgkmcnt(5)
	v_mfma_f32_16x16x32_bf16 v[82:85], v[32:35], v[114:117], v[82:85]
	v_mfma_f32_16x16x32_bf16 v[40:43], v[36:39], v[114:117], v[78:81]
	ds_read_b128 v[114:117], v67 offset:9280
	s_nop 2
	s_waitcnt lgkmcnt(5)
	v_mfma_f32_16x16x32_bf16 v[90:93], v[32:35], v[118:121], v[90:93]
	v_mfma_f32_16x16x32_bf16 v[78:81], v[36:39], v[118:121], v[86:89]
	ds_read_b128 v[118:121], v67 offset:13888
	s_nop 2
	s_waitcnt lgkmcnt(5)
	v_mfma_f32_16x16x32_bf16 v[98:101], v[32:35], v[134:137], v[98:101]
	v_mfma_f32_16x16x32_bf16 v[86:89], v[36:39], v[134:137], v[94:97]
	ds_read_b128 v[134:137], v67 offset:128
	s_nop 2
	s_waitcnt lgkmcnt(9)
	v_mfma_f32_16x16x32_bf16 v[70:73], v[138:141], v[130:133], v[70:73]
	ds_read_b128 v[138:141], v67 offset:4736
	s_waitcnt lgkmcnt(6)
	v_mfma_f32_16x16x32_bf16 v[32:35], v[32:35], v[146:149], v[70:73]
	v_mfma_f32_16x16x32_bf16 v[74:77], v[142:145], v[130:133], v[74:77]
	ds_read_b128 v[142:145], v67 offset:9344
	ds_read_b128 v[130:133], v67 offset:13952
	s_nop 4
	v_mfma_f32_16x16x32_bf16 v[36:39], v[36:39], v[146:149], v[74:77]
	ds_read_b128 v[146:149], v67 offset:192
	s_waitcnt lgkmcnt(8)
	v_mfma_f32_16x16x32_bf16 v[74:77], v[24:27], v[122:125], v[82:85]
	v_mfma_f32_16x16x32_bf16 v[40:43], v[28:31], v[122:125], v[40:43]
	ds_read_b128 v[122:125], v67 offset:4800
	s_waitcnt lgkmcnt(8)
	v_mfma_f32_16x16x32_bf16 v[82:85], v[24:27], v[126:129], v[90:93]
	v_mfma_f32_16x16x32_bf16 v[70:73], v[28:31], v[126:129], v[78:81]
	ds_read_b128 v[126:129], v67 offset:9408
	s_nop 2
	s_waitcnt lgkmcnt(8)
	v_mfma_f32_16x16x32_bf16 v[90:93], v[24:27], v[114:117], v[98:101]
	v_mfma_f32_16x16x32_bf16 v[78:81], v[28:31], v[114:117], v[86:89]
	ds_read_b128 v[114:117], v67 offset:14016
	s_nop 2
	s_waitcnt lgkmcnt(8)
	v_mfma_f32_16x16x32_bf16 v[24:27], v[24:27], v[118:121], v[32:35]
	s_nop 2
	v_mfma_f32_16x16x32_bf16 v[28:31], v[28:31], v[118:121], v[36:39]
	s_waitcnt lgkmcnt(7)
	v_mfma_f32_16x16x32_bf16 v[36:39], v[16:19], v[134:137], v[74:77]
	v_mfma_f32_16x16x32_bf16 v[32:35], v[20:23], v[134:137], v[40:43]
	s_nop 2
	s_waitcnt lgkmcnt(6)
	v_mfma_f32_16x16x32_bf16 v[74:77], v[16:19], v[138:141], v[82:85]
	v_mfma_f32_16x16x32_bf16 v[70:73], v[20:23], v[138:141], v[70:73]
	s_waitcnt lgkmcnt(5)
	v_mfma_f32_16x16x32_bf16 v[82:85], v[16:19], v[142:145], v[90:93]
	v_mfma_f32_16x16x32_bf16 v[78:81], v[20:23], v[142:145], v[78:81]
	s_waitcnt lgkmcnt(4)
	v_mfma_f32_16x16x32_bf16 v[86:89], v[20:23], v[130:133], v[28:31]
	v_mfma_f32_16x16x32_bf16 v[16:19], v[16:19], v[130:133], v[24:27]
	s_waitcnt lgkmcnt(3)
	v_mfma_f32_16x16x32_bf16 v[40:43], v[8:11], v[146:149], v[36:39]
	v_mfma_f32_16x16x32_bf16 v[36:39], v[12:15], v[146:149], v[32:35]
	s_waitcnt lgkmcnt(2)
	v_mfma_f32_16x16x32_bf16 v[32:35], v[8:11], v[122:125], v[74:77]
	v_mfma_f32_16x16x32_bf16 v[28:31], v[12:15], v[122:125], v[70:73]
	s_nop 1
	s_waitcnt lgkmcnt(1)
	v_mfma_f32_16x16x32_bf16 v[24:27], v[8:11], v[126:129], v[82:85]
	v_mfma_f32_16x16x32_bf16 v[20:23], v[12:15], v[126:129], v[78:81]
	s_waitcnt lgkmcnt(0)
	v_mfma_f32_16x16x32_bf16 v[16:19], v[8:11], v[114:117], v[16:19]
	v_mfma_f32_16x16x32_bf16 v[8:11], v[12:15], v[114:117], v[86:89]
	v_cndmask_b32_e32 v12, v178, v179, vcc
	v_cmp_lt_i32_e32 vcc, v187, v180
	v_lshlrev_b32_e32 v13, 2, v12
	v_lshlrev_b32_e32 v15, 2, v47
	v_cndmask_b32_e32 v12, v178, v187, vcc
	v_lshlrev_b32_e32 v14, 2, v12
	v_and_b32_e32 v12, 0x3fffffc0, v55
	v_lshlrev_b32_e32 v12, 2, v12
	v_add3_u32 v12, s0, v12, v15
	v_mul_f32_e32 v15, v41, v41
	v_mul_f32_e32 v55, v43, v43
	v_fmac_f32_e32 v15, v40, v40
	v_fmac_f32_e32 v55, v42, v42
	v_cmp_eq_u32_e32 vcc, 0, v61
	v_add_f32_e32 v15, v15, v55
	v_mul_f32_e32 v55, v37, v37
	v_mul_f32_e32 v61, v39, v39
	v_fmac_f32_e32 v55, v36, v36
	v_fmac_f32_e32 v61, v38, v38
	v_add_f32_e32 v55, v55, v61
	v_add_f32_e32 v15, v15, v55
	ds_bpermute_b32 v55, v13, v15
	s_waitcnt lgkmcnt(0)
	v_add_f32_e32 v15, v15, v55
	ds_bpermute_b32 v55, v14, v15
	s_and_saveexec_b64 s[36:37], vcc
	s_cbranch_execz .LBB0_82
	s_waitcnt lgkmcnt(0)
	v_add_f32_e32 v15, v15, v55
	ds_write_b32 v12, v15
